# softmax row-max butterflies (xor 16/32) in both SWA instances via v_permlane16_swap/v_permlane32_swap instead of ds_bpermute (bit-identical)
# speedup vs baseline: 1.0095x; 1.0053x over previous
; #define MFMA16(a, b, c) __builtin_amdgcn_mfma_f32_16x16x32_bf16((a), (b), (c), 0, 0, 0)
; #define LBAR() do { asm volatile("s_waitcnt lgkmcnt(0)" ::: "memory"); __builtin_amdgcn_s_barrier(); asm volatile("" ::: "memory"); } while (0)
; __device__ __forceinline__ void swa_compute(SwaRaw& R, int b, int kvh, int nb, const bf16_t* P, const float* __restrict__ qg, const float* __restrict__ kg, const float* __restrict__ sinks, bf16_t* OB, LAS unsigned char* lds, int tid) {
;     ...
;         LBAR();
;         f32x4 s[10];
; #pragma unroll
;         for (int j = 0; j < 10; ++j) { f32x4 acc = {0.f, 0.f, 0.f, 0.f};
; #pragma unroll
;             for (int ks = 0; ks < 2; ++ks) acc = MFMA16(ldfrag(Ks, 72, (kt0 + j) * 16 + fr, ks * 32 + 8 * fq), ldfrag(Qs, 72, wid * 16 + fr, ks * 32 + 8 * fq), acc);
;             s[j] = acc; }
;         const int qi = wid * 16 + fr; const float sink = sinks[hq]; float m = sink;
; #pragma unroll
;         for (int j = 0; j < 10; ++j)
; #pragma unroll
;             for (int r = 0; r < 4; ++r) { const int ki = (kt0 + j) * 16 + 4 * fq + r; const bool valid = (ki > qi) && (ki <= qi + 128) && ((nb > 0) || (ki >= 128));
;                 s[j][r] = valid ? s[j][r] : -INFINITY; m = fmaxf(m, s[j][r]); }
;         m = fmaxf(m, __shfl_xor(m, 16)); m = fmaxf(m, __shfl_xor(m, 32));
.LBB0_405:
	s_waitcnt lgkmcnt(0)
	s_barrier
	s_load_dword s99, s[2:3], 0x0
	ds_read_b128 v[16:19], v67 offset:18432
	ds_read_b128 v[80:83], v68
	ds_read_b128 v[20:23], v67 offset:18496
	ds_read_b128 v[84:87], v68 offset:64
	s_waitcnt lgkmcnt(2)
	v_mfma_f32_16x16x32_bf16 v[16:19], v[16:19], v[80:83], 0
	s_waitcnt lgkmcnt(0)
	v_mfma_f32_16x16x32_bf16 v[52:55], v[20:23], v[84:87], v[16:19]
	ds_read_b128 v[20:23], v69 offset:18496
	s_nop 4
	ds_read_b128 v[16:19], v69 offset:18432
	s_waitcnt lgkmcnt(0)
	v_mfma_f32_16x16x32_bf16 v[16:19], v[16:19], v[80:83], 0
	v_cndmask_b32_e64 v52, v201, v52, s[4:5]
	v_cndmask_b32_e64 v53, v201, v53, s[6:7]
	v_cndmask_b32_e64 v54, v201, v54, s[8:9]
	v_mfma_f32_16x16x32_bf16 v[48:51], v[20:23], v[84:87], v[16:19]
	ds_read_b128 v[20:23], v70 offset:18496
	v_cndmask_b32_e64 v55, v201, v55, s[10:11]
	s_nop 1
	ds_read_b128 v[16:19], v70 offset:18432
	s_waitcnt lgkmcnt(0)
	v_mfma_f32_16x16x32_bf16 v[16:19], v[16:19], v[80:83], 0
	s_nop 0
	v_cndmask_b32_e64 v48, v201, v48, s[12:13]
	v_cndmask_b32_e64 v49, v201, v49, s[14:15]
	v_cndmask_b32_e64 v50, v201, v50, s[16:17]
	v_mfma_f32_16x16x32_bf16 v[44:47], v[20:23], v[84:87], v[16:19]
	ds_read_b128 v[20:23], v71 offset:18496
	v_cndmask_b32_e64 v51, v201, v51, s[18:19]
	s_nop 0
	ds_read_b128 v[16:19], v71 offset:18432
	s_waitcnt lgkmcnt(0)
	v_mfma_f32_16x16x32_bf16 v[16:19], v[16:19], v[80:83], 0
	s_nop 1
	v_cndmask_b32_e64 v44, v201, v44, s[20:21]
	v_cndmask_b32_e64 v45, v201, v45, s[22:23]
	v_cndmask_b32_e64 v46, v201, v46, s[24:25]
	v_mfma_f32_16x16x32_bf16 v[40:43], v[20:23], v[84:87], v[16:19]
	ds_read_b128 v[20:23], v72 offset:18496
	v_cndmask_b32_e64 v47, v201, v47, s[26:27]
	s_nop 0
	ds_read_b128 v[16:19], v72 offset:18432
	s_waitcnt lgkmcnt(0)
	v_mfma_f32_16x16x32_bf16 v[16:19], v[16:19], v[80:83], 0
	s_nop 1
	v_cndmask_b32_e64 v40, v201, v40, s[28:29]
	v_cndmask_b32_e64 v41, v201, v41, s[30:31]
	v_cndmask_b32_e64 v42, v201, v42, s[34:35]
	v_mfma_f32_16x16x32_bf16 v[36:39], v[20:23], v[84:87], v[16:19]
	ds_read_b128 v[20:23], v73 offset:18496
	v_cndmask_b32_e64 v43, v201, v43, s[36:37]
	s_nop 0
	ds_read_b128 v[16:19], v73 offset:18432
	s_waitcnt lgkmcnt(0)
	v_mfma_f32_16x16x32_bf16 v[16:19], v[16:19], v[80:83], 0
	s_nop 1
	v_cndmask_b32_e64 v36, v201, v36, s[38:39]
	v_cndmask_b32_e64 v37, v201, v37, s[40:41]
	v_cndmask_b32_e64 v38, v201, v38, s[42:43]
	v_mfma_f32_16x16x32_bf16 v[32:35], v[20:23], v[84:87], v[16:19]
	ds_read_b128 v[20:23], v74 offset:18496
	v_cndmask_b32_e64 v39, v201, v39, s[44:45]
	s_nop 0
	ds_read_b128 v[16:19], v74 offset:18432
	s_waitcnt lgkmcnt(0)
	v_mfma_f32_16x16x32_bf16 v[16:19], v[16:19], v[80:83], 0
	s_nop 1
	v_cndmask_b32_e64 v32, v201, v32, s[46:47]
	v_cndmask_b32_e64 v33, v201, v33, s[48:49]
	v_cndmask_b32_e64 v34, v201, v34, s[50:51]
	v_mfma_f32_16x16x32_bf16 v[28:31], v[20:23], v[84:87], v[16:19]
	ds_read_b128 v[20:23], v75 offset:18496
	v_cndmask_b32_e64 v35, v201, v35, s[52:53]
	s_nop 0
	ds_read_b128 v[16:19], v75 offset:18432
	s_waitcnt lgkmcnt(0)
	v_mfma_f32_16x16x32_bf16 v[16:19], v[16:19], v[80:83], 0
	s_nop 1
	v_cndmask_b32_e64 v28, v201, v28, s[54:55]
	v_cndmask_b32_e64 v29, v201, v29, s[56:57]
	v_cndmask_b32_e64 v30, v201, v30, s[58:59]
	v_mfma_f32_16x16x32_bf16 v[24:27], v[20:23], v[84:87], v[16:19]
	ds_read_b128 v[20:23], v76 offset:18496
	v_cndmask_b32_e64 v31, v201, v31, s[60:61]
	s_nop 0
	ds_read_b128 v[16:19], v76 offset:18432
	s_waitcnt lgkmcnt(0)
	v_mfma_f32_16x16x32_bf16 v[16:19], v[16:19], v[80:83], 0
	s_nop 1
	v_cndmask_b32_e64 v24, v201, v24, s[62:63]
	v_cndmask_b32_e64 v25, v201, v25, s[64:65]
	v_cndmask_b32_e64 v26, v201, v26, s[66:67]
	v_mfma_f32_16x16x32_bf16 v[20:23], v[20:23], v[84:87], v[16:19]
	v_cndmask_b32_e64 v27, v201, v27, s[68:69]
	s_nop 1
	ds_read_b128 v[16:19], v77 offset:18432
	s_waitcnt lgkmcnt(0)
	v_mfma_f32_16x16x32_bf16 v[16:19], v[16:19], v[80:83], 0
	ds_read_b128 v[80:83], v77 offset:18496
	s_nop 0
	v_cndmask_b32_e64 v20, v201, v20, s[70:71]
	v_cndmask_b32_e64 v21, v201, v21, s[72:73]
	s_waitcnt lgkmcnt(0)
	v_mfma_f32_16x16x32_bf16 v[16:19], v[80:83], v[84:87], v[16:19]
	v_cndmask_b32_e64 v22, v201, v22, s[74:75]
	v_cndmask_b32_e64 v23, v201, v23, s[76:77]
	s_nop 4
	v_cndmask_b32_e64 v82, v201, v16, s[78:79]
	v_cndmask_b32_e64 v17, v201, v17, s[80:81]
	v_cndmask_b32_e64 v83, v201, v19, s[84:85]
	s_waitcnt lgkmcnt(0)
	v_mov_b32_e32 v80, s99
	v_max3_f32 v81, v80, v52, v53
	v_max3_f32 v81, v81, v54, v55
	v_max3_f32 v81, v81, v48, v49
	v_max3_f32 v81, v81, v50, v51
	v_max3_f32 v81, v81, v44, v45
	v_max3_f32 v81, v81, v46, v47
	v_max3_f32 v81, v81, v40, v41
	v_max3_f32 v81, v81, v42, v43
	v_max3_f32 v81, v81, v36, v37
	v_max3_f32 v81, v81, v38, v39
	v_max3_f32 v81, v81, v32, v33
	v_max3_f32 v81, v81, v34, v35
	v_max3_f32 v81, v81, v28, v29
	v_max3_f32 v81, v81, v30, v31
	v_max3_f32 v81, v81, v24, v25
	v_max3_f32 v81, v81, v26, v27
	v_max3_f32 v81, v81, v20, v21
	v_max3_f32 v81, v81, v22, v23
	v_max3_f32 v16, v81, v82, v17
	v_cndmask_b32_e64 v81, v201, v18, s[82:83]
	v_max3_f32 v16, v16, v81, v83
	v_mov_b32_e32 v18, v16
	s_nop 1
	v_permlane16_swap_b32_e32 v16, v18
	s_waitcnt lgkmcnt(0)
	v_max_f32_e32 v18, v18, v18
	v_max_f32_e32 v16, v16, v18
	v_mov_b32_e32 v18, v16
	s_nop 1
	v_permlane32_swap_b32_e32 v16, v18
	s_waitcnt lgkmcnt(0)
; __device__ __forceinline__ unsigned cvt_pk_bf16(float lo, float hi) { unsigned r; asm volatile("v_cvt_pk_bf16_f32 %0, %1, %2" : "=v"(r) : "v"(lo), "v"(hi)); return r; }
; #define LAS __attribute__((address_space(3)))
; __device__ __forceinline__ void swa_compute(SwaRaw& R, int b, int kvh, int nb, const bf16_t* P, const float* __restrict__ qg, const float* __restrict__ kg, const float* __restrict__ sinks, bf16_t* OB, LAS unsigned char* lds, int tid) {
;     ...
;         float sum = 0.f;
; #pragma unroll
;         for (int j = 0; j < 10; ++j) {
; #pragma unroll
;             for (int r = 0; r < 4; ++r) { s[j][r] = __expf(s[j][r] - m); sum += s[j][r]; }
;             u32x2 w; w.x = cvt_pk_bf16(s[j][0], s[j][1]); w.y = cvt_pk_bf16(s[j][2], s[j][3]);
;             *(LAS u32x2*)(Pw + fr * 168 + j * 16 + 4 * fq) = w; }
;         sum += __shfl_xor(sum, 16); sum += __shfl_xor(sum, 32);
	v_max_f32_e32 v18, v18, v18
	v_max_f32_e32 v16, v16, v18
	v_sub_f32_e32 v18, v52, v16
	v_mul_f32_e32 v18, 0x3fb8aa3b, v18
	v_sub_f32_e32 v52, v53, v16
	v_exp_f32_e32 v18, v18
	v_mul_f32_e32 v52, 0x3fb8aa3b, v52
	v_sub_f32_e32 v53, v54, v16
	v_exp_f32_e32 v52, v52
	v_mul_f32_e32 v53, 0x3fb8aa3b, v53
	v_sub_f32_e32 v54, v55, v16
	v_exp_f32_e32 v53, v53
	v_mul_f32_e32 v54, 0x3fb8aa3b, v54
	v_exp_f32_e32 v54, v54
	v_add_f32_e32 v19, 0, v18
	v_add_f32_e32 v19, v52, v19
	v_add_f32_e32 v19, v53, v19
	v_cvt_pk_bf16_f32 v18, v18, v52
	v_add_f32_e32 v55, v54, v19
	v_cvt_pk_bf16_f32 v19, v53, v54
	ds_write_b64 v63, v[18:19]
	v_sub_f32_e32 v18, v48, v16
	v_mul_f32_e32 v18, 0x3fb8aa3b, v18
	v_sub_f32_e32 v48, v49, v16
	v_exp_f32_e32 v18, v18
	v_mul_f32_e32 v48, 0x3fb8aa3b, v48
	v_sub_f32_e32 v49, v50, v16
	v_exp_f32_e32 v48, v48
	v_mul_f32_e32 v49, 0x3fb8aa3b, v49
	v_sub_f32_e32 v50, v51, v16
	v_exp_f32_e32 v49, v49
	v_mul_f32_e32 v50, 0x3fb8aa3b, v50
	v_exp_f32_e32 v50, v50
	v_add_f32_e32 v19, v18, v55
	v_add_f32_e32 v19, v48, v19
	v_add_f32_e32 v19, v49, v19
	v_cvt_pk_bf16_f32 v18, v18, v48
	v_add_f32_e32 v51, v50, v19
	v_cvt_pk_bf16_f32 v19, v49, v50
	ds_write_b64 v63, v[18:19] offset:32
	v_sub_f32_e32 v18, v44, v16
	v_mul_f32_e32 v18, 0x3fb8aa3b, v18
	v_sub_f32_e32 v44, v45, v16
	v_exp_f32_e32 v18, v18
	v_mul_f32_e32 v44, 0x3fb8aa3b, v44
	v_sub_f32_e32 v45, v46, v16
	v_exp_f32_e32 v44, v44
	v_mul_f32_e32 v45, 0x3fb8aa3b, v45
	v_sub_f32_e32 v46, v47, v16
	v_exp_f32_e32 v45, v45
	v_mul_f32_e32 v46, 0x3fb8aa3b, v46
	v_exp_f32_e32 v46, v46
	v_add_f32_e32 v19, v18, v51
	v_add_f32_e32 v19, v44, v19
	v_add_f32_e32 v19, v45, v19
	v_cvt_pk_bf16_f32 v18, v18, v44
	v_add_f32_e32 v47, v46, v19
	v_cvt_pk_bf16_f32 v19, v45, v46
	ds_write_b64 v63, v[18:19] offset:64
	v_sub_f32_e32 v18, v40, v16
	v_mul_f32_e32 v18, 0x3fb8aa3b, v18
	v_sub_f32_e32 v40, v41, v16
	v_exp_f32_e32 v18, v18
	v_mul_f32_e32 v40, 0x3fb8aa3b, v40
	v_sub_f32_e32 v41, v42, v16
	v_exp_f32_e32 v40, v40
	v_mul_f32_e32 v41, 0x3fb8aa3b, v41
	v_sub_f32_e32 v42, v43, v16
	v_exp_f32_e32 v41, v41
	v_mul_f32_e32 v42, 0x3fb8aa3b, v42
	v_exp_f32_e32 v42, v42
	v_add_f32_e32 v19, v18, v47
	v_add_f32_e32 v19, v40, v19
	v_add_f32_e32 v19, v41, v19
	v_cvt_pk_bf16_f32 v18, v18, v40
	v_add_f32_e32 v43, v42, v19
	v_cvt_pk_bf16_f32 v19, v41, v42
	ds_write_b64 v63, v[18:19] offset:96
	v_sub_f32_e32 v18, v36, v16
	v_mul_f32_e32 v18, 0x3fb8aa3b, v18
	v_sub_f32_e32 v36, v37, v16
	v_exp_f32_e32 v18, v18
	v_mul_f32_e32 v36, 0x3fb8aa3b, v36
	v_sub_f32_e32 v37, v38, v16
	v_exp_f32_e32 v36, v36
	v_mul_f32_e32 v37, 0x3fb8aa3b, v37
	v_sub_f32_e32 v38, v39, v16
	v_exp_f32_e32 v37, v37
	v_mul_f32_e32 v38, 0x3fb8aa3b, v38
	v_exp_f32_e32 v38, v38
	v_add_f32_e32 v19, v18, v43
	v_add_f32_e32 v19, v36, v19
	v_add_f32_e32 v19, v37, v19
	v_cvt_pk_bf16_f32 v18, v18, v36
	v_add_f32_e32 v39, v38, v19
	v_cvt_pk_bf16_f32 v19, v37, v38
	ds_write_b64 v63, v[18:19] offset:128
	v_sub_f32_e32 v18, v32, v16
	v_mul_f32_e32 v18, 0x3fb8aa3b, v18
	v_sub_f32_e32 v32, v33, v16
	v_exp_f32_e32 v18, v18
	v_mul_f32_e32 v32, 0x3fb8aa3b, v32
	v_sub_f32_e32 v33, v34, v16
	v_exp_f32_e32 v32, v32
	v_mul_f32_e32 v33, 0x3fb8aa3b, v33
	v_sub_f32_e32 v34, v35, v16
	v_exp_f32_e32 v33, v33
	v_mul_f32_e32 v34, 0x3fb8aa3b, v34
	v_exp_f32_e32 v34, v34
	v_add_f32_e32 v19, v18, v39
	v_add_f32_e32 v19, v32, v19
	v_add_f32_e32 v19, v33, v19
	v_cvt_pk_bf16_f32 v18, v18, v32
	v_add_f32_e32 v35, v34, v19
	v_cvt_pk_bf16_f32 v19, v33, v34
	ds_write_b64 v63, v[18:19] offset:160
	v_sub_f32_e32 v18, v28, v16
	v_mul_f32_e32 v18, 0x3fb8aa3b, v18
	v_sub_f32_e32 v28, v29, v16
	v_exp_f32_e32 v18, v18
	v_mul_f32_e32 v28, 0x3fb8aa3b, v28
	v_sub_f32_e32 v29, v30, v16
	v_exp_f32_e32 v28, v28
	v_mul_f32_e32 v29, 0x3fb8aa3b, v29
	v_sub_f32_e32 v30, v31, v16
	v_exp_f32_e32 v29, v29
	v_mul_f32_e32 v30, 0x3fb8aa3b, v30
	v_exp_f32_e32 v30, v30
	v_add_f32_e32 v19, v18, v35
	v_add_f32_e32 v19, v28, v19
	v_add_f32_e32 v19, v29, v19
	v_cvt_pk_bf16_f32 v18, v18, v28
	v_add_f32_e32 v31, v30, v19
	v_cvt_pk_bf16_f32 v19, v29, v30
	ds_write_b64 v63, v[18:19] offset:192
	v_sub_f32_e32 v18, v24, v16
	v_mul_f32_e32 v18, 0x3fb8aa3b, v18
	v_sub_f32_e32 v24, v25, v16
	v_exp_f32_e32 v18, v18
	v_mul_f32_e32 v24, 0x3fb8aa3b, v24
	v_sub_f32_e32 v25, v26, v16
	v_exp_f32_e32 v24, v24
	v_mul_f32_e32 v25, 0x3fb8aa3b, v25
	v_sub_f32_e32 v26, v27, v16
	v_exp_f32_e32 v25, v25
	v_mul_f32_e32 v26, 0x3fb8aa3b, v26
	v_exp_f32_e32 v26, v26
	v_add_f32_e32 v19, v18, v31
	v_add_f32_e32 v19, v24, v19
	v_add_f32_e32 v19, v25, v19
	v_cvt_pk_bf16_f32 v18, v18, v24
	v_add_f32_e32 v27, v26, v19
	v_cvt_pk_bf16_f32 v19, v25, v26
	ds_write_b64 v63, v[18:19] offset:224
	v_sub_f32_e32 v18, v20, v16
	v_mul_f32_e32 v18, 0x3fb8aa3b, v18
	v_sub_f32_e32 v20, v21, v16
	v_exp_f32_e32 v18, v18
	v_mul_f32_e32 v20, 0x3fb8aa3b, v20
	v_sub_f32_e32 v21, v22, v16
	v_exp_f32_e32 v20, v20
	v_mul_f32_e32 v21, 0x3fb8aa3b, v21
	v_sub_f32_e32 v22, v23, v16
	v_exp_f32_e32 v21, v21
	v_mul_f32_e32 v22, 0x3fb8aa3b, v22
	v_exp_f32_e32 v22, v22
	v_add_f32_e32 v19, v18, v27
	v_add_f32_e32 v19, v20, v19
	v_add_f32_e32 v19, v21, v19
	v_cvt_pk_bf16_f32 v18, v18, v20
	v_add_f32_e32 v23, v22, v19
	v_cvt_pk_bf16_f32 v19, v21, v22
	ds_write_b64 v63, v[18:19] offset:256
	v_sub_f32_e32 v18, v82, v16
	v_mul_f32_e32 v18, 0x3fb8aa3b, v18
	v_sub_f32_e32 v17, v17, v16
	v_exp_f32_e32 v18, v18
	v_mul_f32_e32 v17, 0x3fb8aa3b, v17
	v_sub_f32_e32 v20, v81, v16
	v_exp_f32_e32 v17, v17
	v_mul_f32_e32 v20, 0x3fb8aa3b, v20
	v_sub_f32_e32 v21, v83, v16
	v_exp_f32_e32 v20, v20
	v_mul_f32_e32 v21, 0x3fb8aa3b, v21
	v_exp_f32_e32 v21, v21
	v_add_f32_e32 v19, v18, v23
	v_add_f32_e32 v19, v17, v19
	v_add_f32_e32 v19, v20, v19
	v_add_f32_e32 v22, v21, v19
	v_cvt_pk_bf16_f32 v18, v18, v17
	ds_bpermute_b32 v17, v65, v22
	v_cvt_pk_bf16_f32 v19, v20, v21
	ds_write_b64 v63, v[18:19] offset:288
	v_sub_f32_e32 v16, v80, v16
	v_mul_f32_e32 v16, 0x3fb8aa3b, v16
	s_waitcnt lgkmcnt(1)
; __device__ __forceinline__ unsigned cvt_pk_bf16(float lo, float hi) { unsigned r; asm volatile("v_cvt_pk_bf16_f32 %0, %1, %2" : "=v"(r) : "v"(lo), "v"(hi)); return r; }
; #define LAS __attribute__((address_space(3)))
; #define MFMA16(a, b, c) __builtin_amdgcn_mfma_f32_16x16x32_bf16((a), (b), (c), 0, 0, 0)
; #define LBAR() do { asm volatile("s_waitcnt lgkmcnt(0)" ::: "memory"); __builtin_amdgcn_s_barrier(); asm volatile("" ::: "memory"); } while (0)
; __device__ __forceinline__ void swa_compute(SwaRaw& R, int b, int kvh, int nb, const bf16_t* P, const float* __restrict__ qg, const float* __restrict__ kg, const float* __restrict__ sinks, bf16_t* OB, LAS unsigned char* lds, int tid) {
;     ...
;         sum += __shfl_xor(sum, 16); sum += __shfl_xor(sum, 32);
;         const float inv = 1.0f / (sum + __expf(sink - m));
;         asm volatile("s_waitcnt lgkmcnt(0)" ::: "memory"); __builtin_amdgcn_wave_barrier();
; #pragma unroll
;         for (int dt = 0; dt < 4; ++dt) { f32x4 acc = {0.f, 0.f, 0.f, 0.f};
; #pragma unroll
;             for (int ks = 0; ks < 5; ++ks) { const LAS bf16_t* vp = Vr + (kt0 * 16 + ks * 32 + 8 * fq + (fr >> 2)) * 72 + dt * 16 + 4 * (fr & 3);
;                 const v4i16_t lo = __builtin_amdgcn_ds_read_tr16_b64_v4i16((LAS v4i16_t*)vp), hi = __builtin_amdgcn_ds_read_tr16_b64_v4i16((LAS v4i16_t*)(vp + 4 * 72));
;                 const bf16x8 vf = {lo[0], lo[1], lo[2], lo[3], hi[0], hi[1], hi[2], hi[3]};
;                 acc = MFMA16(vf, ldfrag(Pw, 168, fr, ks * 32 + 8 * fq), acc); }
;             u32x2 w; w.x = cvt_pk_bf16(acc[0] * inv, acc[1] * inv); w.y = cvt_pk_bf16(acc[2] * inv, acc[3] * inv);
;             *(u32x2*)(OB + (rq0 + qi) * 1024 + hq * 64 + dt * 16 + 4 * fq) = w; }
;         LBAR();
;     }
	v_add_f32_e32 v17, v22, v17
	ds_bpermute_b32 v18, v66, v17
	v_exp_f32_e32 v16, v16
	v_add_u32_e32 v31, v193, v64
	v_add_u32_e32 v32, v63, v94
	s_waitcnt lgkmcnt(0)
	s_waitcnt lgkmcnt(0)
	v_add_f32_e32 v17, v17, v18
	v_add_f32_e32 v16, v16, v17
	v_div_scale_f32 v17, s[88:89], v16, v16, 1.0
	v_rcp_f32_e32 v18, v17
	s_nop 0
	v_fma_f32 v19, -v17, v18, 1.0
	v_fmac_f32_e32 v18, v19, v18
	v_div_scale_f32 v19, vcc, 1.0, v16, 1.0
	v_mul_f32_e32 v20, v19, v18
	v_fma_f32 v21, -v17, v20, v19
	v_fmac_f32_e32 v20, v21, v18
	v_fma_f32 v17, -v17, v20, v19
	v_div_fmas_f32 v17, v17, v18, v20
	ds_read_b64_tr_b16 v[18:19], v31 offset:55296
	ds_read_b64_tr_b16 v[20:21], v31 offset:55872
	ds_read_b128 v[22:25], v32
	s_waitcnt lgkmcnt(0)
	v_mfma_f32_16x16x32_bf16 v[18:21], v[18:21], v[22:25], 0
	ds_read_b64_tr_b16 v[22:23], v31 offset:59904
	ds_read_b64_tr_b16 v[24:25], v31 offset:60480
	ds_read_b128 v[26:29], v32 offset:64
	v_div_fixup_f32 v30, v17, v16, 1.0
	v_lshl_add_u64 v[16:17], v[58:59], 0, s[96:97]
	s_waitcnt lgkmcnt(0)
	v_mfma_f32_16x16x32_bf16 v[18:21], v[22:25], v[26:29], v[18:21]
	ds_read_b64_tr_b16 v[22:23], v31 offset:64512
	ds_read_b64_tr_b16 v[24:25], v31 offset:65088
	ds_read_b128 v[26:29], v32 offset:128
	s_add_u32 s96, s96, 0x80
	s_addc_u32 s97, s97, 0
	s_waitcnt lgkmcnt(0)
	v_mfma_f32_16x16x32_bf16 v[18:21], v[22:25], v[26:29], v[18:21]
	ds_read_b64_tr_b16 v[22:23], v78 offset:55296
	ds_read_b64_tr_b16 v[24:25], v78 offset:55872
	ds_read_b128 v[26:29], v32 offset:192
	s_add_u32 s2, s2, 4
	s_addc_u32 s3, s3, 0
	s_waitcnt lgkmcnt(0)
	v_mfma_f32_16x16x32_bf16 v[18:21], v[22:25], v[26:29], v[18:21]
	ds_read_b64_tr_b16 v[22:23], v79 offset:55296
	ds_read_b64_tr_b16 v[24:25], v79 offset:55872
	ds_read_b128 v[26:29], v32 offset:256
	s_cmpk_lg_i32 s96, 0x200
	s_waitcnt lgkmcnt(0)
	v_mfma_f32_16x16x32_bf16 v[18:21], v[22:25], v[26:29], v[18:21]
	s_nop 7
	v_mul_f32_e32 v18, v18, v30
	v_mul_f32_e32 v19, v19, v30
	v_cvt_pk_bf16_f32 v18, v18, v19
	v_mul_f32_e32 v19, v20, v30
	v_mul_f32_e32 v20, v21, v30
	v_cvt_pk_bf16_f32 v19, v19, v20
	global_store_dwordx2 v[16:17], v[18:19], off offset:-64
	ds_read_b64_tr_b16 v[18:19], v31 offset:55328
	ds_read_b64_tr_b16 v[20:21], v31 offset:55904
	ds_read_b128 v[22:25], v32
	s_waitcnt lgkmcnt(0)
	v_mfma_f32_16x16x32_bf16 v[18:21], v[18:21], v[22:25], 0
	ds_read_b64_tr_b16 v[22:23], v31 offset:59936
	ds_read_b64_tr_b16 v[24:25], v31 offset:60512
	ds_read_b128 v[26:29], v32 offset:64
	s_waitcnt lgkmcnt(0)
	v_mfma_f32_16x16x32_bf16 v[18:21], v[22:25], v[26:29], v[18:21]
	ds_read_b64_tr_b16 v[22:23], v31 offset:64544
	ds_read_b64_tr_b16 v[24:25], v31 offset:65120
	ds_read_b128 v[26:29], v32 offset:128
	s_waitcnt lgkmcnt(0)
	v_mfma_f32_16x16x32_bf16 v[18:21], v[22:25], v[26:29], v[18:21]
	ds_read_b64_tr_b16 v[22:23], v78 offset:55328
	ds_read_b64_tr_b16 v[24:25], v78 offset:55904
	ds_read_b128 v[26:29], v32 offset:192
	s_waitcnt lgkmcnt(0)
	v_mfma_f32_16x16x32_bf16 v[18:21], v[22:25], v[26:29], v[18:21]
	ds_read_b64_tr_b16 v[22:23], v79 offset:55328
	ds_read_b64_tr_b16 v[24:25], v79 offset:55904
	ds_read_b128 v[26:29], v32 offset:256
	s_waitcnt lgkmcnt(0)
	v_mfma_f32_16x16x32_bf16 v[18:21], v[22:25], v[26:29], v[18:21]
	s_nop 7
	v_mul_f32_e32 v18, v18, v30
	v_mul_f32_e32 v19, v19, v30
	v_cvt_pk_bf16_f32 v18, v18, v19
	v_mul_f32_e32 v19, v20, v30
	v_mul_f32_e32 v20, v21, v30
	v_cvt_pk_bf16_f32 v19, v19, v20
	global_store_dwordx2 v[16:17], v[18:19], off offset:-32
	ds_read_b64_tr_b16 v[18:19], v31 offset:55360
	ds_read_b64_tr_b16 v[20:21], v31 offset:55936
	ds_read_b128 v[22:25], v32
	s_waitcnt lgkmcnt(0)
	v_mfma_f32_16x16x32_bf16 v[18:21], v[18:21], v[22:25], 0
	ds_read_b64_tr_b16 v[22:23], v31 offset:59968
	ds_read_b64_tr_b16 v[24:25], v31 offset:60544
	ds_read_b128 v[26:29], v32 offset:64
	s_waitcnt lgkmcnt(0)
	v_mfma_f32_16x16x32_bf16 v[18:21], v[22:25], v[26:29], v[18:21]
	ds_read_b64_tr_b16 v[22:23], v31 offset:64576
	ds_read_b64_tr_b16 v[24:25], v31 offset:65152
	ds_read_b128 v[26:29], v32 offset:128
	s_waitcnt lgkmcnt(0)
	v_mfma_f32_16x16x32_bf16 v[18:21], v[22:25], v[26:29], v[18:21]
	ds_read_b64_tr_b16 v[22:23], v78 offset:55360
	ds_read_b64_tr_b16 v[24:25], v78 offset:55936
	ds_read_b128 v[26:29], v32 offset:192
	s_waitcnt lgkmcnt(0)
	v_mfma_f32_16x16x32_bf16 v[18:21], v[22:25], v[26:29], v[18:21]
	ds_read_b64_tr_b16 v[22:23], v79 offset:55360
	ds_read_b64_tr_b16 v[24:25], v79 offset:55936
	ds_read_b128 v[26:29], v32 offset:256
	s_waitcnt lgkmcnt(0)
	v_mfma_f32_16x16x32_bf16 v[18:21], v[22:25], v[26:29], v[18:21]
	s_nop 7
	v_mul_f32_e32 v18, v30, v18
	v_mul_f32_e32 v19, v30, v19
	v_cvt_pk_bf16_f32 v18, v18, v19
	v_mul_f32_e32 v19, v30, v20
	v_mul_f32_e32 v20, v30, v21
	v_cvt_pk_bf16_f32 v19, v19, v20
	global_store_dwordx2 v[16:17], v[18:19], off
	ds_read_b64_tr_b16 v[18:19], v31 offset:55392
	ds_read_b64_tr_b16 v[20:21], v31 offset:55968
	ds_read_b128 v[22:25], v32
	s_waitcnt lgkmcnt(0)
	v_mfma_f32_16x16x32_bf16 v[18:21], v[18:21], v[22:25], 0
	ds_read_b64_tr_b16 v[22:23], v31 offset:60000
	ds_read_b64_tr_b16 v[24:25], v31 offset:60576
	ds_read_b128 v[26:29], v32 offset:64
	s_waitcnt lgkmcnt(0)
	v_mfma_f32_16x16x32_bf16 v[18:21], v[22:25], v[26:29], v[18:21]
	ds_read_b64_tr_b16 v[22:23], v31 offset:64608
	ds_read_b64_tr_b16 v[24:25], v31 offset:65184
	ds_read_b128 v[26:29], v32 offset:128
	s_waitcnt lgkmcnt(0)
	v_mfma_f32_16x16x32_bf16 v[18:21], v[22:25], v[26:29], v[18:21]
	ds_read_b64_tr_b16 v[22:23], v78 offset:55392
	ds_read_b64_tr_b16 v[24:25], v78 offset:55968
	ds_read_b128 v[26:29], v32 offset:192
	s_waitcnt lgkmcnt(0)
	v_mfma_f32_16x16x32_bf16 v[18:21], v[22:25], v[26:29], v[18:21]
	ds_read_b64_tr_b16 v[22:23], v79 offset:55392
	ds_read_b64_tr_b16 v[24:25], v79 offset:55968
	ds_read_b128 v[26:29], v32 offset:256
	s_waitcnt lgkmcnt(0)
	v_mfma_f32_16x16x32_bf16 v[18:21], v[22:25], v[26:29], v[18:21]
	s_nop 7
	v_mul_f32_e32 v18, v30, v18
	v_mul_f32_e32 v19, v30, v19
	v_cvt_pk_bf16_f32 v18, v18, v19
	v_mul_f32_e32 v19, v30, v20
	v_mul_f32_e32 v20, v30, v21
	v_cvt_pk_bf16_f32 v19, v19, v20
	global_store_dwordx2 v[16:17], v[18:19], off offset:32
	s_waitcnt lgkmcnt(0)
	s_barrier
	s_cbranch_scc0 .LBB0_392

; #define MFMA16(a, b, c) __builtin_amdgcn_mfma_f32_16x16x32_bf16((a), (b), (c), 0, 0, 0)
; #define LBAR() do { asm volatile("s_waitcnt lgkmcnt(0)" ::: "memory"); __builtin_amdgcn_s_barrier(); asm volatile("" ::: "memory"); } while (0)
; __device__ __forceinline__ void swa_compute(SwaRaw& R, int b, int kvh, int nb, const bf16_t* P, const float* __restrict__ qg, const float* __restrict__ kg, const float* __restrict__ sinks, bf16_t* OB, LAS unsigned char* lds, int tid) {
;     ...
;         LBAR();
;         f32x4 s[10];
; #pragma unroll
;         for (int j = 0; j < 10; ++j) { f32x4 acc = {0.f, 0.f, 0.f, 0.f};
; #pragma unroll
;             for (int ks = 0; ks < 2; ++ks) acc = MFMA16(ldfrag(Ks, 72, (kt0 + j) * 16 + fr, ks * 32 + 8 * fq), ldfrag(Qs, 72, wid * 16 + fr, ks * 32 + 8 * fq), acc);
;             s[j] = acc; }
;         const int qi = wid * 16 + fr; const float sink = sinks[hq]; float m = sink;
; #pragma unroll
;         for (int j = 0; j < 10; ++j)
; #pragma unroll
;             for (int r = 0; r < 4; ++r) { const int ki = (kt0 + j) * 16 + 4 * fq + r; const bool valid = (ki > qi) && (ki <= qi + 128) && ((nb > 0) || (ki >= 128));
;                 s[j][r] = valid ? s[j][r] : -INFINITY; m = fmaxf(m, s[j][r]); }
;         m = fmaxf(m, __shfl_xor(m, 16)); m = fmaxf(m, __shfl_xor(m, 32));
.LBB0_498:
	s_waitcnt lgkmcnt(0)
	s_barrier
	s_load_dword s99, s[2:3], 0x0
	ds_read_b128 v[18:21], v0 offset:18432
	ds_read_b128 v[82:85], v67
	ds_read_b128 v[22:25], v0 offset:18496
	ds_read_b128 v[122:125], v67 offset:64
	s_waitcnt lgkmcnt(2)
	v_mfma_f32_16x16x32_bf16 v[18:21], v[18:21], v[82:85], 0
	s_waitcnt lgkmcnt(0)
	v_mfma_f32_16x16x32_bf16 v[54:57], v[22:25], v[122:125], v[18:21]
	ds_read_b128 v[22:25], v68 offset:18496
	s_nop 4
	ds_read_b128 v[18:21], v68 offset:18432
	s_waitcnt lgkmcnt(0)
	v_mfma_f32_16x16x32_bf16 v[18:21], v[18:21], v[82:85], 0
	v_cndmask_b32_e64 v54, v177, v54, s[4:5]
	v_cndmask_b32_e64 v55, v177, v55, s[6:7]
	v_cndmask_b32_e64 v56, v177, v56, s[8:9]
	v_mfma_f32_16x16x32_bf16 v[50:53], v[22:25], v[122:125], v[18:21]
	ds_read_b128 v[22:25], v69 offset:18496
	v_cndmask_b32_e64 v57, v177, v57, s[10:11]
	s_nop 1
	ds_read_b128 v[18:21], v69 offset:18432
	s_waitcnt lgkmcnt(0)
	v_mfma_f32_16x16x32_bf16 v[18:21], v[18:21], v[82:85], 0
	s_nop 0
	v_cndmask_b32_e64 v50, v177, v50, s[12:13]
	v_cndmask_b32_e64 v51, v177, v51, s[14:15]
	v_cndmask_b32_e64 v52, v177, v52, s[16:17]
	v_mfma_f32_16x16x32_bf16 v[46:49], v[22:25], v[122:125], v[18:21]
	ds_read_b128 v[22:25], v70 offset:18496
	v_cndmask_b32_e64 v53, v177, v53, s[18:19]
	s_nop 0
	ds_read_b128 v[18:21], v70 offset:18432
	s_waitcnt lgkmcnt(0)
	v_mfma_f32_16x16x32_bf16 v[18:21], v[18:21], v[82:85], 0
	s_nop 1
	v_cndmask_b32_e64 v46, v177, v46, s[20:21]
	v_cndmask_b32_e64 v47, v177, v47, s[22:23]
	v_cndmask_b32_e64 v48, v177, v48, s[24:25]
	v_mfma_f32_16x16x32_bf16 v[42:45], v[22:25], v[122:125], v[18:21]
	ds_read_b128 v[22:25], v71 offset:18496
	v_cndmask_b32_e64 v49, v177, v49, s[26:27]
	s_nop 0
	ds_read_b128 v[18:21], v71 offset:18432
	s_waitcnt lgkmcnt(0)
	v_mfma_f32_16x16x32_bf16 v[18:21], v[18:21], v[82:85], 0
	s_nop 1
	v_cndmask_b32_e64 v42, v177, v42, s[28:29]
	v_cndmask_b32_e64 v43, v177, v43, s[30:31]
	v_cndmask_b32_e64 v44, v177, v44, s[34:35]
	v_mfma_f32_16x16x32_bf16 v[38:41], v[22:25], v[122:125], v[18:21]
	ds_read_b128 v[22:25], v72 offset:18496
	v_cndmask_b32_e64 v45, v177, v45, s[36:37]
	s_nop 0
	ds_read_b128 v[18:21], v72 offset:18432
	s_waitcnt lgkmcnt(0)
	v_mfma_f32_16x16x32_bf16 v[18:21], v[18:21], v[82:85], 0
	s_nop 1
	v_cndmask_b32_e64 v38, v177, v38, s[38:39]
	v_cndmask_b32_e64 v39, v177, v39, s[40:41]
	v_cndmask_b32_e64 v40, v177, v40, s[42:43]
	v_mfma_f32_16x16x32_bf16 v[34:37], v[22:25], v[122:125], v[18:21]
	ds_read_b128 v[22:25], v73 offset:18496
	v_cndmask_b32_e64 v41, v177, v41, s[44:45]
	s_nop 0
	ds_read_b128 v[18:21], v73 offset:18432
	s_waitcnt lgkmcnt(0)
	v_mfma_f32_16x16x32_bf16 v[18:21], v[18:21], v[82:85], 0
	s_nop 1
	v_cndmask_b32_e64 v34, v177, v34, s[46:47]
	v_cndmask_b32_e64 v35, v177, v35, s[48:49]
	v_cndmask_b32_e64 v36, v177, v36, s[50:51]
	v_mfma_f32_16x16x32_bf16 v[30:33], v[22:25], v[122:125], v[18:21]
	ds_read_b128 v[22:25], v76 offset:18496
	v_cndmask_b32_e64 v37, v177, v37, s[52:53]
	s_nop 0
	ds_read_b128 v[18:21], v76 offset:18432
	s_waitcnt lgkmcnt(0)
	v_mfma_f32_16x16x32_bf16 v[18:21], v[18:21], v[82:85], 0
	s_nop 1
	v_cndmask_b32_e64 v30, v177, v30, s[54:55]
	v_cndmask_b32_e64 v31, v177, v31, s[56:57]
	v_cndmask_b32_e64 v32, v177, v32, s[58:59]
	v_mfma_f32_16x16x32_bf16 v[26:29], v[22:25], v[122:125], v[18:21]
	ds_read_b128 v[22:25], v77 offset:18496
	v_cndmask_b32_e64 v33, v177, v33, s[60:61]
	s_nop 0
	ds_read_b128 v[18:21], v77 offset:18432
	s_waitcnt lgkmcnt(0)
	v_mfma_f32_16x16x32_bf16 v[18:21], v[18:21], v[82:85], 0
	s_nop 1
	v_cndmask_b32_e64 v26, v177, v26, s[62:63]
	v_cndmask_b32_e64 v27, v177, v27, s[64:65]
	v_cndmask_b32_e64 v28, v177, v28, s[66:67]
	v_mfma_f32_16x16x32_bf16 v[22:25], v[22:25], v[122:125], v[18:21]
	v_cndmask_b32_e64 v29, v177, v29, s[68:69]
	s_nop 1
	ds_read_b128 v[18:21], v78 offset:18432
	s_waitcnt lgkmcnt(0)
	v_mfma_f32_16x16x32_bf16 v[18:21], v[18:21], v[82:85], 0
	ds_read_b128 v[82:85], v78 offset:18496
	s_nop 0
	v_cndmask_b32_e64 v22, v177, v22, s[70:71]
	v_cndmask_b32_e64 v23, v177, v23, s[72:73]
	s_waitcnt lgkmcnt(0)
	v_mfma_f32_16x16x32_bf16 v[18:21], v[82:85], v[122:125], v[18:21]
	s_waitcnt lgkmcnt(0)
	v_mov_b32_e32 v81, s99
	v_max3_f32 v82, v81, v54, v55
	v_max3_f32 v82, v82, v56, v57
	v_max3_f32 v82, v82, v50, v51
	v_max3_f32 v82, v82, v52, v53
	v_max3_f32 v82, v82, v46, v47
	v_max3_f32 v82, v82, v48, v49
	v_max3_f32 v82, v82, v42, v43
	v_max3_f32 v82, v82, v44, v45
	v_max3_f32 v82, v82, v38, v39
	v_max3_f32 v82, v82, v40, v41
	v_max3_f32 v82, v82, v34, v35
	v_max3_f32 v82, v82, v36, v37
	v_max3_f32 v82, v82, v30, v31
	v_max3_f32 v82, v82, v32, v33
	v_max3_f32 v82, v82, v26, v27
	v_max3_f32 v82, v82, v28, v29
	v_max3_f32 v82, v82, v22, v23
	v_cndmask_b32_e64 v24, v177, v24, s[74:75]
	v_cndmask_b32_e64 v25, v177, v25, s[76:77]
	v_max3_f32 v82, v82, v24, v25
	v_cndmask_b32_e64 v83, v177, v18, s[78:79]
	v_cndmask_b32_e64 v19, v177, v19, s[80:81]
	v_max3_f32 v18, v82, v83, v19
	v_cndmask_b32_e64 v82, v177, v20, s[82:83]
	v_cndmask_b32_e64 v84, v177, v21, s[84:85]
	v_max3_f32 v18, v18, v82, v84
	v_mov_b32_e32 v20, v18
	s_nop 1
	v_permlane16_swap_b32_e32 v18, v20
	s_waitcnt lgkmcnt(0)
	v_max_f32_e32 v20, v20, v20
	v_max_f32_e32 v18, v18, v20
	v_mov_b32_e32 v20, v18
	s_nop 1
	v_permlane32_swap_b32_e32 v18, v20
	s_waitcnt lgkmcnt(0)
; __device__ __forceinline__ unsigned cvt_pk_bf16(float lo, float hi) { unsigned r; asm volatile("v_cvt_pk_bf16_f32 %0, %1, %2" : "=v"(r) : "v"(lo), "v"(hi)); return r; }
; #define LAS __attribute__((address_space(3)))
; __device__ __forceinline__ void swa_compute(SwaRaw& R, int b, int kvh, int nb, const bf16_t* P, const float* __restrict__ qg, const float* __restrict__ kg, const float* __restrict__ sinks, bf16_t* OB, LAS unsigned char* lds, int tid) {
;     ...
;         float sum = 0.f;
; #pragma unroll
;         for (int j = 0; j < 10; ++j) {
; #pragma unroll
;             for (int r = 0; r < 4; ++r) { s[j][r] = __expf(s[j][r] - m); sum += s[j][r]; }
;             u32x2 w; w.x = cvt_pk_bf16(s[j][0], s[j][1]); w.y = cvt_pk_bf16(s[j][2], s[j][3]);
;             *(LAS u32x2*)(Pw + fr * 168 + j * 16 + 4 * fq) = w; }
;         sum += __shfl_xor(sum, 16); sum += __shfl_xor(sum, 32);
	v_max_f32_e32 v20, v20, v20
	v_max_f32_e32 v18, v18, v20
	v_sub_f32_e32 v20, v54, v18
	v_mul_f32_e32 v20, 0x3fb8aa3b, v20
	v_sub_f32_e32 v54, v55, v18
	v_exp_f32_e32 v20, v20
	v_mul_f32_e32 v54, 0x3fb8aa3b, v54
	v_sub_f32_e32 v55, v56, v18
	v_exp_f32_e32 v54, v54
	v_mul_f32_e32 v55, 0x3fb8aa3b, v55
	v_sub_f32_e32 v56, v57, v18
	v_exp_f32_e32 v55, v55
	v_mul_f32_e32 v56, 0x3fb8aa3b, v56
	v_exp_f32_e32 v56, v56
	v_add_f32_e32 v21, 0, v20
	v_add_f32_e32 v21, v54, v21
	v_add_f32_e32 v21, v55, v21
	v_cvt_pk_bf16_f32 v20, v20, v54
	v_add_f32_e32 v57, v56, v21
	v_cvt_pk_bf16_f32 v21, v55, v56
	ds_write_b64 v65, v[20:21]
	v_sub_f32_e32 v20, v50, v18
	v_mul_f32_e32 v20, 0x3fb8aa3b, v20
	v_sub_f32_e32 v50, v51, v18
	v_exp_f32_e32 v20, v20
	v_mul_f32_e32 v50, 0x3fb8aa3b, v50
	v_sub_f32_e32 v51, v52, v18
	v_exp_f32_e32 v50, v50
	v_mul_f32_e32 v51, 0x3fb8aa3b, v51
	v_sub_f32_e32 v52, v53, v18
	v_exp_f32_e32 v51, v51
	v_mul_f32_e32 v52, 0x3fb8aa3b, v52
	v_exp_f32_e32 v52, v52
	v_add_f32_e32 v21, v20, v57
	v_add_f32_e32 v21, v50, v21
	v_add_f32_e32 v21, v51, v21
	v_cvt_pk_bf16_f32 v20, v20, v50
	v_add_f32_e32 v53, v52, v21
	v_cvt_pk_bf16_f32 v21, v51, v52
	ds_write_b64 v65, v[20:21] offset:32
	v_sub_f32_e32 v20, v46, v18
	v_mul_f32_e32 v20, 0x3fb8aa3b, v20
	v_sub_f32_e32 v46, v47, v18
	v_exp_f32_e32 v20, v20
	v_mul_f32_e32 v46, 0x3fb8aa3b, v46
	v_sub_f32_e32 v47, v48, v18
	v_exp_f32_e32 v46, v46
	v_mul_f32_e32 v47, 0x3fb8aa3b, v47
	v_sub_f32_e32 v48, v49, v18
	v_exp_f32_e32 v47, v47
	v_mul_f32_e32 v48, 0x3fb8aa3b, v48
	v_exp_f32_e32 v48, v48
	v_add_f32_e32 v21, v20, v53
	v_add_f32_e32 v21, v46, v21
	v_add_f32_e32 v21, v47, v21
	v_cvt_pk_bf16_f32 v20, v20, v46
	v_add_f32_e32 v49, v48, v21
	v_cvt_pk_bf16_f32 v21, v47, v48
	ds_write_b64 v65, v[20:21] offset:64
	v_sub_f32_e32 v20, v42, v18
	v_mul_f32_e32 v20, 0x3fb8aa3b, v20
	v_sub_f32_e32 v42, v43, v18
	v_exp_f32_e32 v20, v20
	v_mul_f32_e32 v42, 0x3fb8aa3b, v42
	v_sub_f32_e32 v43, v44, v18
	v_exp_f32_e32 v42, v42
	v_mul_f32_e32 v43, 0x3fb8aa3b, v43
	v_sub_f32_e32 v44, v45, v18
	v_exp_f32_e32 v43, v43
	v_mul_f32_e32 v44, 0x3fb8aa3b, v44
	v_exp_f32_e32 v44, v44
	v_add_f32_e32 v21, v20, v49
	v_add_f32_e32 v21, v42, v21
	v_add_f32_e32 v21, v43, v21
	v_cvt_pk_bf16_f32 v20, v20, v42
	v_add_f32_e32 v45, v44, v21
	v_cvt_pk_bf16_f32 v21, v43, v44
	ds_write_b64 v65, v[20:21] offset:96
	v_sub_f32_e32 v20, v38, v18
	v_mul_f32_e32 v20, 0x3fb8aa3b, v20
	v_sub_f32_e32 v38, v39, v18
	v_exp_f32_e32 v20, v20
	v_mul_f32_e32 v38, 0x3fb8aa3b, v38
	v_sub_f32_e32 v39, v40, v18
	v_exp_f32_e32 v38, v38
	v_mul_f32_e32 v39, 0x3fb8aa3b, v39
	v_sub_f32_e32 v40, v41, v18
	v_exp_f32_e32 v39, v39
	v_mul_f32_e32 v40, 0x3fb8aa3b, v40
	v_exp_f32_e32 v40, v40
	v_add_f32_e32 v21, v20, v45
	v_add_f32_e32 v21, v38, v21
	v_add_f32_e32 v21, v39, v21
	v_cvt_pk_bf16_f32 v20, v20, v38
	v_add_f32_e32 v41, v40, v21
	v_cvt_pk_bf16_f32 v21, v39, v40
	ds_write_b64 v65, v[20:21] offset:128
	v_sub_f32_e32 v20, v34, v18
	v_mul_f32_e32 v20, 0x3fb8aa3b, v20
	v_sub_f32_e32 v34, v35, v18
	v_exp_f32_e32 v20, v20
	v_mul_f32_e32 v34, 0x3fb8aa3b, v34
	v_sub_f32_e32 v35, v36, v18
	v_exp_f32_e32 v34, v34
	v_mul_f32_e32 v35, 0x3fb8aa3b, v35
	v_sub_f32_e32 v36, v37, v18
	v_exp_f32_e32 v35, v35
	v_mul_f32_e32 v36, 0x3fb8aa3b, v36
	v_exp_f32_e32 v36, v36
	v_add_f32_e32 v21, v20, v41
	v_add_f32_e32 v21, v34, v21
	v_add_f32_e32 v21, v35, v21
	v_cvt_pk_bf16_f32 v20, v20, v34
	v_add_f32_e32 v37, v36, v21
	v_cvt_pk_bf16_f32 v21, v35, v36
	ds_write_b64 v65, v[20:21] offset:160
	v_sub_f32_e32 v20, v30, v18
	v_mul_f32_e32 v20, 0x3fb8aa3b, v20
	v_sub_f32_e32 v30, v31, v18
	v_exp_f32_e32 v20, v20
	v_mul_f32_e32 v30, 0x3fb8aa3b, v30
	v_sub_f32_e32 v31, v32, v18
	v_exp_f32_e32 v30, v30
	v_mul_f32_e32 v31, 0x3fb8aa3b, v31
	v_sub_f32_e32 v32, v33, v18
	v_exp_f32_e32 v31, v31
	v_mul_f32_e32 v32, 0x3fb8aa3b, v32
	v_exp_f32_e32 v32, v32
	v_add_f32_e32 v21, v20, v37
	v_add_f32_e32 v21, v30, v21
	v_add_f32_e32 v21, v31, v21
	v_cvt_pk_bf16_f32 v20, v20, v30
	v_add_f32_e32 v33, v32, v21
	v_cvt_pk_bf16_f32 v21, v31, v32
	ds_write_b64 v65, v[20:21] offset:192
	v_sub_f32_e32 v20, v26, v18
	v_mul_f32_e32 v20, 0x3fb8aa3b, v20
	v_sub_f32_e32 v26, v27, v18
	v_exp_f32_e32 v20, v20
	v_mul_f32_e32 v26, 0x3fb8aa3b, v26
	v_sub_f32_e32 v27, v28, v18
	v_exp_f32_e32 v26, v26
	v_mul_f32_e32 v27, 0x3fb8aa3b, v27
	v_sub_f32_e32 v28, v29, v18
	v_exp_f32_e32 v27, v27
	v_mul_f32_e32 v28, 0x3fb8aa3b, v28
	v_exp_f32_e32 v28, v28
	v_add_f32_e32 v21, v20, v33
	v_add_f32_e32 v21, v26, v21
	v_add_f32_e32 v21, v27, v21
	v_cvt_pk_bf16_f32 v20, v20, v26
	v_add_f32_e32 v29, v28, v21
	v_cvt_pk_bf16_f32 v21, v27, v28
	ds_write_b64 v65, v[20:21] offset:224
	v_sub_f32_e32 v20, v22, v18
	v_mul_f32_e32 v20, 0x3fb8aa3b, v20
	v_sub_f32_e32 v22, v23, v18
	v_exp_f32_e32 v20, v20
	v_mul_f32_e32 v22, 0x3fb8aa3b, v22
	v_sub_f32_e32 v23, v24, v18
	v_exp_f32_e32 v22, v22
	v_mul_f32_e32 v23, 0x3fb8aa3b, v23
	v_sub_f32_e32 v24, v25, v18
	v_exp_f32_e32 v23, v23
	v_mul_f32_e32 v24, 0x3fb8aa3b, v24
	v_exp_f32_e32 v24, v24
	v_add_f32_e32 v21, v20, v29
	v_add_f32_e32 v21, v22, v21
	v_add_f32_e32 v21, v23, v21
	v_cvt_pk_bf16_f32 v20, v20, v22
	v_add_f32_e32 v25, v24, v21
	v_cvt_pk_bf16_f32 v21, v23, v24
	ds_write_b64 v65, v[20:21] offset:256
	v_sub_f32_e32 v20, v83, v18
	v_mul_f32_e32 v20, 0x3fb8aa3b, v20
	v_sub_f32_e32 v19, v19, v18
	v_exp_f32_e32 v20, v20
	v_mul_f32_e32 v19, 0x3fb8aa3b, v19
	v_sub_f32_e32 v22, v82, v18
	v_exp_f32_e32 v19, v19
	v_mul_f32_e32 v22, 0x3fb8aa3b, v22
	v_sub_f32_e32 v23, v84, v18
	v_exp_f32_e32 v22, v22
	v_mul_f32_e32 v23, 0x3fb8aa3b, v23
	v_exp_f32_e32 v23, v23
	v_add_f32_e32 v21, v20, v25
	v_add_f32_e32 v21, v19, v21
	v_add_f32_e32 v21, v22, v21
	v_add_f32_e32 v24, v23, v21
	v_cvt_pk_bf16_f32 v20, v20, v19
	ds_bpermute_b32 v19, v74, v24
	v_cvt_pk_bf16_f32 v21, v22, v23
	ds_write_b64 v65, v[20:21] offset:288
	v_sub_f32_e32 v18, v81, v18
	v_mul_f32_e32 v18, 0x3fb8aa3b, v18
	s_waitcnt lgkmcnt(1)
; __device__ __forceinline__ unsigned cvt_pk_bf16(float lo, float hi) { unsigned r; asm volatile("v_cvt_pk_bf16_f32 %0, %1, %2" : "=v"(r) : "v"(lo), "v"(hi)); return r; }
; #define LAS __attribute__((address_space(3)))
; #define MFMA16(a, b, c) __builtin_amdgcn_mfma_f32_16x16x32_bf16((a), (b), (c), 0, 0, 0)
; #define LBAR() do { asm volatile("s_waitcnt lgkmcnt(0)" ::: "memory"); __builtin_amdgcn_s_barrier(); asm volatile("" ::: "memory"); } while (0)
; __device__ __forceinline__ void swa_compute(SwaRaw& R, int b, int kvh, int nb, const bf16_t* P, const float* __restrict__ qg, const float* __restrict__ kg, const float* __restrict__ sinks, bf16_t* OB, LAS unsigned char* lds, int tid) {
;     ...
;         sum += __shfl_xor(sum, 16); sum += __shfl_xor(sum, 32);
;         const float inv = 1.0f / (sum + __expf(sink - m));
;         asm volatile("s_waitcnt lgkmcnt(0)" ::: "memory"); __builtin_amdgcn_wave_barrier();
; #pragma unroll
;         for (int dt = 0; dt < 4; ++dt) { f32x4 acc = {0.f, 0.f, 0.f, 0.f};
; #pragma unroll
;             for (int ks = 0; ks < 5; ++ks) { const LAS bf16_t* vp = Vr + (kt0 * 16 + ks * 32 + 8 * fq + (fr >> 2)) * 72 + dt * 16 + 4 * (fr & 3);
;                 const v4i16_t lo = __builtin_amdgcn_ds_read_tr16_b64_v4i16((LAS v4i16_t*)vp), hi = __builtin_amdgcn_ds_read_tr16_b64_v4i16((LAS v4i16_t*)(vp + 4 * 72));
;                 const bf16x8 vf = {lo[0], lo[1], lo[2], lo[3], hi[0], hi[1], hi[2], hi[3]};
;                 acc = MFMA16(vf, ldfrag(Pw, 168, fr, ks * 32 + 8 * fq), acc); }
;             u32x2 w; w.x = cvt_pk_bf16(acc[0] * inv, acc[1] * inv); w.y = cvt_pk_bf16(acc[2] * inv, acc[3] * inv);
;             *(u32x2*)(OB + (rq0 + qi) * 1024 + hq * 64 + dt * 16 + 4 * fq) = w; }
;         LBAR();
;     }
	v_add_f32_e32 v19, v24, v19
	ds_bpermute_b32 v20, v75, v19
	v_exp_f32_e32 v18, v18
	v_add_u32_e32 v33, v165, v66
	v_add_u32_e32 v34, v65, v94
	s_waitcnt lgkmcnt(0)
	s_waitcnt lgkmcnt(0)
	v_add_f32_e32 v19, v19, v20
	v_add_f32_e32 v18, v18, v19
	v_div_scale_f32 v19, s[88:89], v18, v18, 1.0
	v_rcp_f32_e32 v20, v19
	s_nop 0
	v_fma_f32 v21, -v19, v20, 1.0
	v_fmac_f32_e32 v20, v21, v20
	v_div_scale_f32 v21, vcc, 1.0, v18, 1.0
	v_mul_f32_e32 v22, v21, v20
	v_fma_f32 v23, -v19, v22, v21
	v_fmac_f32_e32 v22, v23, v20
	v_fma_f32 v19, -v19, v22, v21
	v_div_fmas_f32 v19, v19, v20, v22
	ds_read_b64_tr_b16 v[20:21], v33 offset:55296
	ds_read_b64_tr_b16 v[22:23], v33 offset:55872
	ds_read_b128 v[24:27], v34
	s_waitcnt lgkmcnt(0)
	v_mfma_f32_16x16x32_bf16 v[20:23], v[20:23], v[24:27], 0
	ds_read_b64_tr_b16 v[24:25], v33 offset:59904
	ds_read_b64_tr_b16 v[26:27], v33 offset:60480
	ds_read_b128 v[28:31], v34 offset:64
	v_div_fixup_f32 v32, v19, v18, 1.0
	v_lshl_add_u64 v[18:19], v[60:61], 0, s[86:87]
	s_waitcnt lgkmcnt(0)
	v_mfma_f32_16x16x32_bf16 v[20:23], v[24:27], v[28:31], v[20:23]
	ds_read_b64_tr_b16 v[24:25], v33 offset:64512
	ds_read_b64_tr_b16 v[26:27], v33 offset:65088
	ds_read_b128 v[28:31], v34 offset:128
	s_add_u32 s86, s86, 0x80
	s_addc_u32 s87, s87, 0
	s_waitcnt lgkmcnt(0)
	v_mfma_f32_16x16x32_bf16 v[20:23], v[24:27], v[28:31], v[20:23]
	ds_read_b64_tr_b16 v[24:25], v79 offset:55296
	ds_read_b64_tr_b16 v[26:27], v79 offset:55872
	ds_read_b128 v[28:31], v34 offset:192
	s_add_u32 s2, s2, 4
	s_addc_u32 s3, s3, 0
	s_waitcnt lgkmcnt(0)
	v_mfma_f32_16x16x32_bf16 v[20:23], v[24:27], v[28:31], v[20:23]
	ds_read_b64_tr_b16 v[24:25], v80 offset:55296
	ds_read_b64_tr_b16 v[26:27], v80 offset:55872
	ds_read_b128 v[28:31], v34 offset:256
	s_cmpk_lg_i32 s86, 0x200
	s_waitcnt lgkmcnt(0)
	v_mfma_f32_16x16x32_bf16 v[20:23], v[24:27], v[28:31], v[20:23]
	s_nop 7
	v_mul_f32_e32 v20, v20, v32
	v_mul_f32_e32 v21, v21, v32
	v_cvt_pk_bf16_f32 v20, v20, v21
	v_mul_f32_e32 v21, v22, v32
	v_mul_f32_e32 v22, v23, v32
	v_cvt_pk_bf16_f32 v21, v21, v22
	global_store_dwordx2 v[18:19], v[20:21], off offset:-64
	ds_read_b64_tr_b16 v[20:21], v33 offset:55328
	ds_read_b64_tr_b16 v[22:23], v33 offset:55904
	ds_read_b128 v[24:27], v34
	s_waitcnt lgkmcnt(0)
	v_mfma_f32_16x16x32_bf16 v[20:23], v[20:23], v[24:27], 0
	ds_read_b64_tr_b16 v[24:25], v33 offset:59936
	ds_read_b64_tr_b16 v[26:27], v33 offset:60512
	ds_read_b128 v[28:31], v34 offset:64
	s_waitcnt lgkmcnt(0)
	v_mfma_f32_16x16x32_bf16 v[20:23], v[24:27], v[28:31], v[20:23]
	ds_read_b64_tr_b16 v[24:25], v33 offset:64544
	ds_read_b64_tr_b16 v[26:27], v33 offset:65120
	ds_read_b128 v[28:31], v34 offset:128
	s_waitcnt lgkmcnt(0)
	v_mfma_f32_16x16x32_bf16 v[20:23], v[24:27], v[28:31], v[20:23]
	ds_read_b64_tr_b16 v[24:25], v79 offset:55328
	ds_read_b64_tr_b16 v[26:27], v79 offset:55904
	ds_read_b128 v[28:31], v34 offset:192
	s_waitcnt lgkmcnt(0)
	v_mfma_f32_16x16x32_bf16 v[20:23], v[24:27], v[28:31], v[20:23]
	ds_read_b64_tr_b16 v[24:25], v80 offset:55328
	ds_read_b64_tr_b16 v[26:27], v80 offset:55904
	ds_read_b128 v[28:31], v34 offset:256
	s_waitcnt lgkmcnt(0)
	v_mfma_f32_16x16x32_bf16 v[20:23], v[24:27], v[28:31], v[20:23]
	s_nop 7
	v_mul_f32_e32 v20, v20, v32
	v_mul_f32_e32 v21, v21, v32
	v_cvt_pk_bf16_f32 v20, v20, v21
	v_mul_f32_e32 v21, v22, v32
	v_mul_f32_e32 v22, v23, v32
	v_cvt_pk_bf16_f32 v21, v21, v22
	global_store_dwordx2 v[18:19], v[20:21], off offset:-32
	ds_read_b64_tr_b16 v[20:21], v33 offset:55360
	ds_read_b64_tr_b16 v[22:23], v33 offset:55936
	ds_read_b128 v[24:27], v34
	s_waitcnt lgkmcnt(0)
	v_mfma_f32_16x16x32_bf16 v[20:23], v[20:23], v[24:27], 0
	ds_read_b64_tr_b16 v[24:25], v33 offset:59968
	ds_read_b64_tr_b16 v[26:27], v33 offset:60544
	ds_read_b128 v[28:31], v34 offset:64
	s_waitcnt lgkmcnt(0)
	v_mfma_f32_16x16x32_bf16 v[20:23], v[24:27], v[28:31], v[20:23]
	ds_read_b64_tr_b16 v[24:25], v33 offset:64576
	ds_read_b64_tr_b16 v[26:27], v33 offset:65152
	ds_read_b128 v[28:31], v34 offset:128
	s_waitcnt lgkmcnt(0)
	v_mfma_f32_16x16x32_bf16 v[20:23], v[24:27], v[28:31], v[20:23]
	ds_read_b64_tr_b16 v[24:25], v79 offset:55360
	ds_read_b64_tr_b16 v[26:27], v79 offset:55936
	ds_read_b128 v[28:31], v34 offset:192
	s_waitcnt lgkmcnt(0)
	v_mfma_f32_16x16x32_bf16 v[20:23], v[24:27], v[28:31], v[20:23]
	ds_read_b64_tr_b16 v[24:25], v80 offset:55360
	ds_read_b64_tr_b16 v[26:27], v80 offset:55936
	ds_read_b128 v[28:31], v34 offset:256
	s_waitcnt lgkmcnt(0)
	v_mfma_f32_16x16x32_bf16 v[20:23], v[24:27], v[28:31], v[20:23]
	s_nop 7
	v_mul_f32_e32 v20, v32, v20
	v_mul_f32_e32 v21, v32, v21
	v_cvt_pk_bf16_f32 v20, v20, v21
	v_mul_f32_e32 v21, v32, v22
	v_mul_f32_e32 v22, v32, v23
	v_cvt_pk_bf16_f32 v21, v21, v22
	global_store_dwordx2 v[18:19], v[20:21], off
	ds_read_b64_tr_b16 v[20:21], v33 offset:55392
	ds_read_b64_tr_b16 v[22:23], v33 offset:55968
	ds_read_b128 v[24:27], v34
	s_waitcnt lgkmcnt(0)
	v_mfma_f32_16x16x32_bf16 v[20:23], v[20:23], v[24:27], 0
	ds_read_b64_tr_b16 v[24:25], v33 offset:60000
	ds_read_b64_tr_b16 v[26:27], v33 offset:60576
	ds_read_b128 v[28:31], v34 offset:64
	s_waitcnt lgkmcnt(0)
	v_mfma_f32_16x16x32_bf16 v[20:23], v[24:27], v[28:31], v[20:23]
	ds_read_b64_tr_b16 v[24:25], v33 offset:64608
	ds_read_b64_tr_b16 v[26:27], v33 offset:65184
	ds_read_b128 v[28:31], v34 offset:128
	s_waitcnt lgkmcnt(0)
	v_mfma_f32_16x16x32_bf16 v[20:23], v[24:27], v[28:31], v[20:23]
	ds_read_b64_tr_b16 v[24:25], v79 offset:55392
	ds_read_b64_tr_b16 v[26:27], v79 offset:55968
	ds_read_b128 v[28:31], v34 offset:192
	s_waitcnt lgkmcnt(0)
	v_mfma_f32_16x16x32_bf16 v[20:23], v[24:27], v[28:31], v[20:23]
	ds_read_b64_tr_b16 v[24:25], v80 offset:55392
	ds_read_b64_tr_b16 v[26:27], v80 offset:55968
	ds_read_b128 v[28:31], v34 offset:256
	s_waitcnt lgkmcnt(0)
	v_mfma_f32_16x16x32_bf16 v[20:23], v[24:27], v[28:31], v[20:23]
	s_nop 7
	v_mul_f32_e32 v20, v32, v20
	v_mul_f32_e32 v21, v32, v21
	v_cvt_pk_bf16_f32 v20, v20, v21
	v_mul_f32_e32 v21, v32, v22
	v_mul_f32_e32 v22, v32, v23
	v_cvt_pk_bf16_f32 v21, v21, v22
	global_store_dwordx2 v[18:19], v[20:21], off offset:32
	s_waitcnt lgkmcnt(0)
	s_barrier
	s_cbranch_scc0 .LBB0_473
